# GEMM peeled k-step 29: dropped compiler vmcnt(0) after the counted vmcnt(6) so the last stage stays in flight
# baseline (speedup 1.0000x reference)
; template <bool IN_PROJ>
; DI void gemm_tile(const Params& p, int layer, int nt, int tt, char* smem) {
;     ...
;   auto stage = [&](int kt) {
;     const int k0 = kt * 32;
;     char* base = smem + (kt % 3) * G_STAGE + w * 1024;
; #pragma unroll
;     for (int i = 0; i < 4; ++i)
;       __builtin_amdgcn_raw_ptr_buffer_load_lds(rA, (lds_ptr_t)(base + i * 4096), 16, voA[i], k0 * 2, 0, 0);
; #pragma unroll
;     for (int i = 0; i < 2; ++i) {
;       lds_ptr_t dst = (lds_ptr_t)(base + 16384 + i * 4096);
;       if (IN_PROJ) __builtin_amdgcn_raw_ptr_buffer_load_lds(rB0, dst, 16, rowB[i] * (DM * 2) + lcB[i], k0 * 2, 0, 0);
;       else {
;         if (k0 < 512) __builtin_amdgcn_raw_ptr_buffer_load_lds(rB0, dst, 16, rowB[i] * 1024 + lcB[i], k0 * 2, 0, 0);
;         else if (k0 < 768) __builtin_amdgcn_raw_ptr_buffer_load_lds(rB1, dst, 16, rowB[i] * 512 + lcB[i], (k0 - 512) * 2, 0, 0);
;         else __builtin_amdgcn_raw_ptr_buffer_load_lds(rB2, dst, 16, rowB[i] * 512 + lcB[i], (k0 - 768) * 2, 0, 0);
;       }
;     }
;   };
;   asm volatile("s_waitcnt vmcnt(0)" ::: "memory");
;   __syncthreads();
;   stage(0); stage(1); stage(2);
;   auto load_frags = [&](int kt, int ks, bf16x8 (&fa)[4], bf16x8 (&fb)[2]) {
;     const u16* sA = (const u16*)(smem + (kt % 3) * G_STAGE);
;     const u16* sB = sA + 8192;
; #pragma unroll
;     for (int fi = 0; fi < 4; ++fi) fa[fi] = *(const bf16x8*)(sA + gswz(wf * 128 + fi * 32 + r, ks * 2 + h));
; #pragma unroll
;     for (int ti = 0; ti < 2; ++ti) fb[ti] = *(const bf16x8*)(sB + gswz(wt * 64 + ti * 32 + r, ks * 2 + h));
;   };
;   auto mma = [&](const bf16x8 (&fa)[4], const bf16x8 (&fb)[2]) {
; #pragma unroll
;     for (int fi = 0; fi < 4; ++fi)
; #pragma unroll
;       for (int ti = 0; ti < 2; ++ti) acc[fi][ti] = MFMA32(fa[fi], fb[ti], acc[fi][ti]);
;   };
;   bf16x8 fa0[4], fb0[2], fa1[4], fb1[2];
;   asm volatile("s_waitcnt vmcnt(12)" ::: "memory");
;   __syncthreads();
;   load_frags(0, 0, fa0, fb0);
;   for (int kt = 0; kt < 32; ++kt) {
;     load_frags(kt, 1, fa1, fb1);
;     mma(fa0, fb0);
;     if (kt + 1 < 32) {
;       if (kt + 2 < 32) asm volatile("s_waitcnt vmcnt(6) lgkmcnt(0)" ::: "memory");
;       else asm volatile("s_waitcnt vmcnt(0) lgkmcnt(0)" ::: "memory");
;       __syncthreads();
;       if (kt + 3 < 32) stage(kt + 3);
;       load_frags(kt + 1, 0, fa0, fb0);
;     }
;     mma(fa1, fb1);
;   }
.LBB0_72:
	s_mul_i32 s3, s0, 0xab
	s_add_i32 s10, s3, 0xfdff
	s_bfe_u32 s10, s10, 0x70009
	s_mul_i32 s10, s10, 3
	s_sub_i32 s10, s0, s10
	s_add_i32 s10, s10, 0xfffd
	s_and_b32 s10, s10, 0xff
	s_mulk_i32 s10, 0x6000
	v_lshl_add_u32 v136, v188, 1, s10
	ds_read_b128 v[172:175], v136
	v_lshl_add_u32 v136, v186, 1, s10
	v_lshl_or_b32 v140, v187, 1, s10
	ds_read_b128 v[168:171], v136 offset:2048
	ds_read_b128 v[164:167], v136 offset:4096
	ds_read_b128 v[136:139], v136 offset:6144
	ds_read_b128 v[160:163], v140 offset:16384
	v_lshl_or_b32 v140, v180, 1, s10
	s_bfe_u32 s10, s3, 0x70009
	s_mul_i32 s10, s10, 3
	s_sub_i32 s10, s0, s10
	s_and_b32 s10, s10, 0xff
	s_mulk_i32 s10, 0x6000
	s_add_i32 s60, s1, s10
	s_mov_b32 m0, s60
	ds_read_b128 v[140:143], v140 offset:18432
	s_waitcnt vmcnt(6) lgkmcnt(0)
	s_waitcnt lgkmcnt(0)
	s_barrier
	buffer_load_dwordx4 v181, s[4:7], s2 offen lds
	s_add_i32 m0, s60, 0x1000
	s_mov_b32 s10, s6
	buffer_load_dwordx4 v182, s[4:7], s2 offen lds
	s_add_i32 m0, s60, 0x2000
	s_mov_b32 s11, s7
	buffer_load_dwordx4 v183, s[4:7], s2 offen lds
	s_add_i32 m0, s60, 0x3000
	v_mfma_f32_32x32x16_bf16 v[64:79], v[132:135], v[128:131], v[64:79]
	buffer_load_dwordx4 v184, s[4:7], s2 offen lds
	s_add_i32 m0, s60, 0x4000
	s_add_i32 s3, s3, 0xfeaa
	buffer_load_dwordx4 v181, s[8:11], s2 offen lds
	s_add_i32 m0, s60, 0x5000
	s_bfe_u32 s3, s3, 0x70009
	buffer_load_dwordx4 v185, s[8:11], s2 offen lds
	v_mfma_f32_32x32x16_bf16 v[0:15], v[132:135], v[108:111], v[0:15]
	s_mul_i32 s3, s3, 3
	s_sub_i32 s3, s0, s3
	s_add_i32 s3, s3, 0xfffe
	s_and_b32 s3, s3, 0xff
	s_mulk_i32 s3, 0x6000
	s_add_i32 s2, s2, 64
	s_add_i32 s0, s0, 1
	v_mfma_f32_32x32x16_bf16 v[80:95], v[104:107], v[128:131], v[80:95]
	s_cmp_eq_u32 s0, 32
	v_mfma_f32_32x32x16_bf16 v[16:31], v[104:107], v[108:111], v[16:31]
	v_mfma_f32_32x32x16_bf16 v[112:127], v[100:103], v[128:131], v[112:127]
	v_mfma_f32_32x32x16_bf16 v[32:47], v[100:103], v[108:111], v[32:47]
	v_mfma_f32_32x32x16_bf16 v[144:159], v[96:99], v[128:131], v[144:159]
	v_mfma_f32_32x32x16_bf16 v[48:63], v[96:99], v[108:111], v[48:63]
	v_lshl_add_u32 v96, v189, 1, s3
	ds_read_b128 v[132:135], v96
	v_lshl_add_u32 v96, v190, 1, s3
	v_lshl_or_b32 v108, v191, 1, s3
	ds_read_b128 v[104:107], v96 offset:2048
	ds_read_b128 v[100:103], v96 offset:4096
	ds_read_b128 v[96:99], v96 offset:6144
	ds_read_b128 v[128:131], v108 offset:16384
	v_lshl_or_b32 v108, v194, 1, s3
	v_mfma_f32_32x32x16_bf16 v[64:79], v[172:175], v[160:163], v[64:79]
	ds_read_b128 v[108:111], v108 offset:18432
	v_mfma_f32_32x32x16_bf16 v[0:15], v[172:175], v[140:143], v[0:15]
	v_mfma_f32_32x32x16_bf16 v[80:95], v[168:171], v[160:163], v[80:95]
	v_mfma_f32_32x32x16_bf16 v[16:31], v[168:171], v[140:143], v[16:31]
	v_mfma_f32_32x32x16_bf16 v[112:127], v[164:167], v[160:163], v[112:127]
	v_mfma_f32_32x32x16_bf16 v[32:47], v[164:167], v[140:143], v[32:47]
	v_mfma_f32_32x32x16_bf16 v[144:159], v[136:139], v[160:163], v[144:159]
	v_mfma_f32_32x32x16_bf16 v[48:63], v[136:139], v[140:143], v[48:63]
	s_cbranch_scc0 .LBB0_72
	s_waitcnt lgkmcnt(1)
	v_mfma_f32_32x32x16_bf16 v[64:79], v[132:135], v[128:131], v[64:79]
	s_lshl_b32 s83, s82, 1
	s_add_i32 s4, s75, s83
	s_cmp_lt_i32 s4, 4
	v_mfma_f32_32x32x16_bf16 v[80:95], v[104:107], v[128:131], v[80:95]
	v_mfma_f32_32x32x16_bf16 v[112:127], v[100:103], v[128:131], v[112:127]
	v_mfma_f32_32x32x16_bf16 v[144:159], v[96:99], v[128:131], v[144:159]
	v_lshlrev_b32_e32 v128, 1, v188
	v_lshlrev_b32_e32 v130, 1, v186
	v_lshlrev_b32_e32 v129, 1, v187
	s_waitcnt lgkmcnt(0)
	v_mfma_f32_32x32x16_bf16 v[16:31], v[104:107], v[108:111], v[16:31]
	ds_read_b128 v[104:107], v130 offset:51200
	v_mfma_f32_32x32x16_bf16 v[32:47], v[100:103], v[108:111], v[32:47]
	ds_read_b128 v[100:103], v128 offset:49152
	v_mfma_f32_32x32x16_bf16 v[0:15], v[132:135], v[108:111], v[0:15]
	v_mfma_f32_32x32x16_bf16 v[48:63], v[96:99], v[108:111], v[48:63]
	v_or_b32_e32 v96, 0x10000, v129
	v_lshl_or_b32 v108, v180, 1, v244
	ds_read_b128 v[96:99], v96
	ds_read_b128 v[108:111], v108
	s_waitcnt lgkmcnt(1)
	v_mfma_f32_32x32x16_bf16 v[64:79], v[100:103], v[96:99], v[64:79]
	s_waitcnt lgkmcnt(0)
	v_mfma_f32_32x32x16_bf16 v[0:15], v[100:103], v[108:111], v[0:15]
	v_mfma_f32_32x32x16_bf16 v[80:95], v[104:107], v[96:99], v[80:95]
	v_mfma_f32_32x32x16_bf16 v[16:31], v[104:107], v[108:111], v[16:31]
	ds_read_b128 v[100:103], v130 offset:53248
	ds_read_b128 v[104:107], v130 offset:55296
	s_waitcnt vmcnt(6) lgkmcnt(0)
	s_waitcnt lgkmcnt(0)
	s_barrier
; DI TileDesc tile_desc(const Params& p, int nt) {
;   TileDesc d; d.aux = 0;
;   char* ws = p.ws; char* o = p.out;
;   if (nt < 4)       { d.kind = K_SILU; d.dst = (u16*)(ws + WS_HQ); d.stride = 512; d.col = nt * 128; }
;   else if (nt < 8)  { d.kind = K_G;    d.dst = (u16*)(ws + WS_GF); d.stride = 512; d.col = (nt - 4) * 128; d.aux = 0; }
;   else if (nt < 12) { d.kind = K_G;    d.dst = (u16*)(ws + WS_GB); d.stride = 512; d.col = (nt - 8) * 128; d.aux = 1; }
;   else if (nt < 16) { d.kind = K_COPY; d.dst = (u16*)(ws + WS_HV); d.stride = 512; d.col = (nt - 12) * 128; }
;   else if (nt < 20) { d.kind = K_SILU; d.dst = (u16*)(o + DO_GA);  d.stride = 512; d.col = (nt - 16) * 128; }
;   else if (nt < 22) { d.kind = K_QN;   d.dst = (u16*)(o + DO_BQ);  d.stride = 256; d.col = (nt - 20) * 128; }
;   else if (nt < 23) { d.kind = K_KN;   d.dst = (u16*)(o + DO_BK);  d.stride = 128; d.col = 0; }
;   else if (nt < 24) { d.kind = K_VT;   d.dst = (u16*)(o + DO_BVT); d.stride = T_TOK; d.col = 0; }
;   else if (nt < 26) { d.kind = K_SILU; d.dst = (u16*)(o + DO_GB);  d.stride = 256; d.col = (nt - 24) * 128; }
;   else if (nt < 28) { d.kind = K_CQ;   d.dst = (u16*)(o + DO_CQ);  d.stride = 256; d.col = (nt - 26) * 128; }
;   else if (nt < 30) { d.kind = K_CK;   d.dst = (u16*)(o + DO_CK);  d.stride = 256; d.col = (nt - 28) * 128; d.aux = (nt - 28); }
;   else if (nt < 32) { d.kind = K_VT;   d.dst = (u16*)(ws + WS_CVT); d.stride = T_TOK; d.col = (nt - 30) * 128; }
;   else              { d.kind = K_SILU; d.dst = (u16*)(o + DO_GC);  d.stride = 256; d.col = (nt - 32) * 128; }
;   return d;
; template <bool IN_PROJ>
; DI void gemm_tile(const Params& p, int layer, int nt, int tt, char* smem) {
;     ...
;   for (int kt = 0; kt < 32; ++kt) {
;     load_frags(kt, 1, fa1, fb1);
;     mma(fa0, fb0);
;     if (kt + 1 < 32) {
;       if (kt + 2 < 32) asm volatile("s_waitcnt vmcnt(6) lgkmcnt(0)" ::: "memory");
;       else asm volatile("s_waitcnt vmcnt(0) lgkmcnt(0)" ::: "memory");
;       __syncthreads();
;       if (kt + 3 < 32) stage(kt + 3);
;       load_frags(kt + 1, 0, fa0, fb0);
;     }
;     mma(fa1, fb1);
;   }
;   __syncthreads();
	v_mfma_f32_32x32x16_bf16 v[112:127], v[100:103], v[96:99], v[112:127]
	v_mfma_f32_32x32x16_bf16 v[32:47], v[100:103], v[108:111], v[32:47]
	v_mfma_f32_32x32x16_bf16 v[144:159], v[104:107], v[96:99], v[144:159]
	ds_read_b128 v[96:99], v177
	ds_read_b128 v[100:103], v178 offset:16384
	v_mfma_f32_32x32x16_bf16 v[48:63], v[104:107], v[108:111], v[48:63]
	ds_read_b128 v[104:107], v179 offset:18432
	v_lshlrev_b32_e32 v108, 1, v180
	s_waitcnt lgkmcnt(1)
	v_mfma_f32_32x32x16_bf16 v[64:79], v[96:99], v[100:103], v[64:79]
	s_waitcnt lgkmcnt(0)
	v_mfma_f32_32x32x16_bf16 v[0:15], v[96:99], v[104:107], v[0:15]
	ds_read_b128 v[96:99], v176 offset:2048
	s_waitcnt lgkmcnt(0)
	v_mfma_f32_32x32x16_bf16 v[80:95], v[96:99], v[100:103], v[80:95]
	v_mfma_f32_32x32x16_bf16 v[16:31], v[96:99], v[104:107], v[16:31]
	ds_read_b128 v[96:99], v176 offset:4096
	s_waitcnt lgkmcnt(0)
	v_mfma_f32_32x32x16_bf16 v[112:127], v[96:99], v[100:103], v[112:127]
	v_mfma_f32_32x32x16_bf16 v[32:47], v[96:99], v[104:107], v[32:47]
	ds_read_b128 v[96:99], v176 offset:6144
	s_waitcnt lgkmcnt(0)
	v_mfma_f32_32x32x16_bf16 v[144:159], v[96:99], v[100:103], v[144:159]
	v_mfma_f32_32x32x16_bf16 v[48:63], v[96:99], v[104:107], v[48:63]
	ds_read_b128 v[96:99], v128
	ds_read_b128 v[100:103], v129 offset:16384
	ds_read_b128 v[104:107], v108 offset:18432
	s_waitcnt lgkmcnt(1)
	v_mfma_f32_32x32x16_bf16 v[64:79], v[96:99], v[100:103], v[64:79]
	s_waitcnt lgkmcnt(0)
	v_mfma_f32_32x32x16_bf16 v[0:15], v[96:99], v[104:107], v[0:15]
	ds_read_b128 v[96:99], v130 offset:2048
	s_waitcnt lgkmcnt(0)
	v_mfma_f32_32x32x16_bf16 v[80:95], v[96:99], v[100:103], v[80:95]
	v_mfma_f32_32x32x16_bf16 v[16:31], v[96:99], v[104:107], v[16:31]
	ds_read_b128 v[96:99], v130 offset:4096
	s_waitcnt lgkmcnt(0)
	v_mfma_f32_32x32x16_bf16 v[112:127], v[96:99], v[100:103], v[112:127]
	v_mfma_f32_32x32x16_bf16 v[32:47], v[96:99], v[104:107], v[32:47]
	ds_read_b128 v[96:99], v130 offset:6144
	s_waitcnt vmcnt(0) lgkmcnt(0)
	s_waitcnt lgkmcnt(0)
	s_barrier
	v_mfma_f32_32x32x16_bf16 v[144:159], v[96:99], v[100:103], v[144:159]
	v_mfma_f32_32x32x16_bf16 v[48:63], v[96:99], v[104:107], v[48:63]
	ds_read_b128 v[96:99], v177 offset:24576
	ds_read_b128 v[100:103], v178 offset:40960
	ds_read_b128 v[104:107], v179 offset:43008
	s_waitcnt lgkmcnt(1)
	v_mfma_f32_32x32x16_bf16 v[64:79], v[96:99], v[100:103], v[64:79]
	s_waitcnt lgkmcnt(0)
	v_mfma_f32_32x32x16_bf16 v[0:15], v[96:99], v[104:107], v[0:15]
	ds_read_b128 v[96:99], v176 offset:26624
	s_waitcnt lgkmcnt(0)
	v_mfma_f32_32x32x16_bf16 v[80:95], v[96:99], v[100:103], v[80:95]
	v_mfma_f32_32x32x16_bf16 v[16:31], v[96:99], v[104:107], v[16:31]
	ds_read_b128 v[96:99], v176 offset:28672
	s_waitcnt lgkmcnt(0)
	v_mfma_f32_32x32x16_bf16 v[112:127], v[96:99], v[100:103], v[112:127]
	v_mfma_f32_32x32x16_bf16 v[32:47], v[96:99], v[104:107], v[32:47]
	ds_read_b128 v[96:99], v176 offset:30720
	s_waitcnt lgkmcnt(0)
	v_mfma_f32_32x32x16_bf16 v[144:159], v[96:99], v[100:103], v[144:159]
	v_mfma_f32_32x32x16_bf16 v[48:63], v[96:99], v[104:107], v[48:63]
	ds_read_b128 v[96:99], v128 offset:24576
	ds_read_b128 v[100:103], v129 offset:40960
	ds_read_b128 v[104:107], v130 offset:26624
	ds_read_b128 v[108:111], v108 offset:43008
	s_waitcnt lgkmcnt(2)
	v_mfma_f32_32x32x16_bf16 v[64:79], v[96:99], v[100:103], v[64:79]
	s_waitcnt lgkmcnt(0)
	v_mfma_f32_32x32x16_bf16 v[0:15], v[96:99], v[108:111], v[0:15]
	v_mfma_f32_32x32x16_bf16 v[80:95], v[104:107], v[100:103], v[80:95]
	v_mfma_f32_32x32x16_bf16 v[16:31], v[104:107], v[108:111], v[16:31]
	ds_read_b128 v[96:99], v130 offset:28672
	ds_read_b128 v[104:107], v130 offset:30720
	s_waitcnt lgkmcnt(0)
	s_barrier
	v_mfma_f32_32x32x16_bf16 v[112:127], v[96:99], v[100:103], v[112:127]
	v_mfma_f32_32x32x16_bf16 v[32:47], v[96:99], v[108:111], v[32:47]
	v_mfma_f32_32x32x16_bf16 v[144:159], v[104:107], v[100:103], v[144:159]
	v_mfma_f32_32x32x16_bf16 v[48:63], v[104:107], v[108:111], v[48:63]
	s_cbranch_scc1 .LBB0_83
	s_cmp_lt_u32 s4, 12
	s_cbranch_scc1 .LBB0_84
	s_mov_b64 s[0:1], 0
	s_mov_b32 s73, 1
	s_cmp_lt_u32 s4, 16
	s_mov_b64 s[2:3], 0
	s_cbranch_scc1 .LBB0_89
	s_cmp_lt_u32 s4, 20
	s_cbranch_scc1 .LBB0_85
	s_cmp_lt_u32 s4, 22
	s_cbranch_scc1 .LBB0_86
	s_cmp_eq_u32 s4, 22
	s_cbranch_scc1 .LBB0_87
	s_cmp_lt_u32 s4, 24
	s_cbranch_scc1 .LBB0_88
	s_cmp_lt_u32 s4, 26
	s_cbranch_scc1 .LBB0_85
	s_cmp_lt_u32 s4, 28
	s_cbranch_scc1 .LBB0_550
	s_cmp_lt_u32 s4, 32
	s_cselect_b32 s5, 5, 0
	s_and_b32 s2, s4, 0x7ffffffe
	s_cmp_eq_u32 s2, 30
	s_cselect_b64 s[2:3], -1, 0
	s_cmp_gt_u32 s4, 29
	s_cselect_b32 s73, s5, 7
	s_branch .LBB0_89

; template <bool IN_PROJ>
; DI void gemm_tile(const Params& p, int layer, int nt, int tt, char* smem) {
;     ...
;   for (int kt = 0; kt < 32; ++kt) {
;     load_frags(kt, 1, fa1, fb1);
;     mma(fa0, fb0);
;     if (kt + 1 < 32) {
;       if (kt + 2 < 32) asm volatile("s_waitcnt vmcnt(6) lgkmcnt(0)" ::: "memory");
;       else asm volatile("s_waitcnt vmcnt(0) lgkmcnt(0)" ::: "memory");
;       __syncthreads();
;       if (kt + 3 < 32) stage(kt + 3);
;       load_frags(kt + 1, 0, fa0, fb0);
;     }
;     mma(fa1, fb1);
;   }
;   __syncthreads();
;   if (!IN_PROJ) {
;     u16* yb = (u16*)(p.ws + WS_Y);
;     u16* sC = (u16*)(smem + wf * 34816);
.LBB0_722:
	s_waitcnt lgkmcnt(1)
	v_mfma_f32_32x32x16_bf16 v[64:79], v[148:151], v[140:143], v[64:79]
	v_lshlrev_b32_e32 v152, 1, v191
	v_lshlrev_b32_e32 v156, 1, v188
	s_mul_i32 s38, s38, 0x8800
	v_lshl_or_b32 v168, v178, 3, s38
	v_mul_u32_u24_e32 v169, 0x88, v179
	v_lshl_add_u32 v168, v169, 1, v168
	s_lshl_b64 s[4:5], s[20:21], 1
	s_waitcnt lgkmcnt(0)
	v_mfma_f32_32x32x16_bf16 v[112:127], v[148:151], v[132:135], v[112:127]
	v_lshlrev_b32_e32 v148, 1, v195
	s_add_u32 s4, s70, s4
	v_and_b32_e32 v172, 0xf0, v172
	s_addc_u32 s5, s71, s5
	v_mfma_f32_32x32x16_bf16 v[96:111], v[144:147], v[140:143], v[96:111]
	v_mfma_f32_32x32x16_bf16 v[80:95], v[144:147], v[132:135], v[80:95]
	v_lshlrev_b32_e32 v144, 1, v192
	v_mfma_f32_32x32x16_bf16 v[48:63], v[136:139], v[140:143], v[48:63]
	v_mfma_f32_32x32x16_bf16 v[32:47], v[136:139], v[132:135], v[32:47]
	ds_read_b128 v[136:139], v144 offset:49152
	v_mfma_f32_32x32x16_bf16 v[0:15], v[128:131], v[132:135], v[0:15]
	ds_read_b128 v[132:135], v148 offset:51200
	v_mfma_f32_32x32x16_bf16 v[16:31], v[128:131], v[140:143], v[16:31]
	v_or_b32_e32 v128, 0x10000, v152
	v_lshl_or_b32 v140, v188, 1, v175
	ds_read_b128 v[128:131], v128
	ds_read_b128 v[140:143], v140
	s_waitcnt lgkmcnt(1)
	v_mfma_f32_32x32x16_bf16 v[64:79], v[136:139], v[128:131], v[64:79]
	s_waitcnt lgkmcnt(0)
	v_mfma_f32_32x32x16_bf16 v[112:127], v[136:139], v[140:143], v[112:127]
	v_mfma_f32_32x32x16_bf16 v[96:111], v[132:135], v[128:131], v[96:111]
	v_mfma_f32_32x32x16_bf16 v[80:95], v[132:135], v[140:143], v[80:95]
	ds_read_b128 v[132:135], v148 offset:53248
	ds_read_b128 v[136:139], v148 offset:55296
	s_waitcnt vmcnt(6) lgkmcnt(0)
	s_waitcnt lgkmcnt(0)
	s_barrier
	v_mfma_f32_32x32x16_bf16 v[48:63], v[132:135], v[128:131], v[48:63]
	v_mfma_f32_32x32x16_bf16 v[32:47], v[132:135], v[140:143], v[32:47]
	v_mfma_f32_32x32x16_bf16 v[16:31], v[136:139], v[128:131], v[16:31]
	ds_read_b128 v[128:131], v181
	ds_read_b128 v[132:135], v182 offset:16384
	v_mfma_f32_32x32x16_bf16 v[0:15], v[136:139], v[140:143], v[0:15]
	ds_read_b128 v[136:139], v183 offset:18432
	s_waitcnt lgkmcnt(1)
	v_mfma_f32_32x32x16_bf16 v[64:79], v[128:131], v[132:135], v[64:79]
	s_waitcnt lgkmcnt(0)
	v_mfma_f32_32x32x16_bf16 v[112:127], v[128:131], v[136:139], v[112:127]
	ds_read_b128 v[128:131], v180 offset:2048
	s_waitcnt lgkmcnt(0)
	v_mfma_f32_32x32x16_bf16 v[96:111], v[128:131], v[132:135], v[96:111]
	v_mfma_f32_32x32x16_bf16 v[80:95], v[128:131], v[136:139], v[80:95]
	ds_read_b128 v[128:131], v180 offset:4096
	s_waitcnt lgkmcnt(0)
	v_mfma_f32_32x32x16_bf16 v[48:63], v[128:131], v[132:135], v[48:63]
	v_mfma_f32_32x32x16_bf16 v[32:47], v[128:131], v[136:139], v[32:47]
	ds_read_b128 v[128:131], v180 offset:6144
	s_waitcnt lgkmcnt(0)
	v_mfma_f32_32x32x16_bf16 v[16:31], v[128:131], v[132:135], v[16:31]
	v_mfma_f32_32x32x16_bf16 v[0:15], v[128:131], v[136:139], v[0:15]
	ds_read_b128 v[128:131], v144
	ds_read_b128 v[132:135], v152 offset:16384
	ds_read_b128 v[136:139], v156 offset:18432
	s_waitcnt lgkmcnt(1)
	v_mfma_f32_32x32x16_bf16 v[64:79], v[128:131], v[132:135], v[64:79]
	s_waitcnt lgkmcnt(0)
	v_mfma_f32_32x32x16_bf16 v[112:127], v[128:131], v[136:139], v[112:127]
	ds_read_b128 v[128:131], v148 offset:2048
	s_waitcnt lgkmcnt(0)
	v_mfma_f32_32x32x16_bf16 v[96:111], v[128:131], v[132:135], v[96:111]
	v_mfma_f32_32x32x16_bf16 v[80:95], v[128:131], v[136:139], v[80:95]
	ds_read_b128 v[128:131], v148 offset:4096
	s_waitcnt lgkmcnt(0)
	v_mfma_f32_32x32x16_bf16 v[48:63], v[128:131], v[132:135], v[48:63]
	v_mfma_f32_32x32x16_bf16 v[32:47], v[128:131], v[136:139], v[32:47]
	ds_read_b128 v[128:131], v148 offset:6144
	s_waitcnt vmcnt(0) lgkmcnt(0)
	s_waitcnt lgkmcnt(0)
	s_barrier
	v_mfma_f32_32x32x16_bf16 v[16:31], v[128:131], v[132:135], v[16:31]
	v_mfma_f32_32x32x16_bf16 v[0:15], v[128:131], v[136:139], v[0:15]
	ds_read_b128 v[128:131], v181 offset:24576
	ds_read_b128 v[132:135], v182 offset:40960
	ds_read_b128 v[136:139], v183 offset:43008
	s_waitcnt lgkmcnt(1)
	v_mfma_f32_32x32x16_bf16 v[64:79], v[128:131], v[132:135], v[64:79]
	s_waitcnt lgkmcnt(0)
	v_mfma_f32_32x32x16_bf16 v[112:127], v[128:131], v[136:139], v[112:127]
	ds_read_b128 v[128:131], v180 offset:26624
	ds_read_b128 v[140:143], v144 offset:24576
	ds_read_b128 v[144:147], v148 offset:26624
	s_waitcnt lgkmcnt(2)
	v_mfma_f32_32x32x16_bf16 v[96:111], v[128:131], v[132:135], v[96:111]
	v_mfma_f32_32x32x16_bf16 v[80:95], v[128:131], v[136:139], v[80:95]
	ds_read_b128 v[128:131], v148 offset:28672
	ds_read_b128 v[148:151], v148 offset:30720
	ds_read_b128 v[152:155], v152 offset:40960
	ds_read_b128 v[156:159], v156 offset:43008
	ds_read_b128 v[160:163], v180 offset:30720
	ds_read_b128 v[164:167], v180 offset:28672
	s_waitcnt lgkmcnt(0)
	s_barrier
; DI u32 pack2bf(float lo, float hi) { f32x2 v = {lo, hi}; return __builtin_bit_cast(u32, __builtin_convertvector(v, bf2_t)); }
; template <bool IN_PROJ>
; DI void gemm_tile(const Params& p, int layer, int nt, int tt, char* smem) {
;     ...
;     mma(fa1, fb1);
;   }
;   __syncthreads();
;   if (!IN_PROJ) {
;     u16* yb = (u16*)(p.ws + WS_Y);
;     u16* sC = (u16*)(smem + wf * 34816);
; #pragma unroll
;     for (int fi = 0; fi < 4; ++fi)
; #pragma unroll
;       for (int ti = 0; ti < 2; ++ti)
; #pragma unroll
;         for (int g = 0; g < 4; ++g) {
;           u32x2 pk = {pack2bf(acc[fi][ti][4 * g], acc[fi][ti][4 * g + 1]), pack2bf(acc[fi][ti][4 * g + 2], acc[fi][ti][4 * g + 3])};
;           *(u32x2*)(sC + (wt * 64 + ti * 32 + r) * CS + fi * 32 + 8 * g + 4 * h) = pk;
;         }
	v_mfma_f32_32x32x16_bf16 v[32:47], v[164:167], v[136:139], v[32:47]
	v_mfma_f32_32x32x16_bf16 v[48:63], v[164:167], v[132:135], v[48:63]
	v_mfma_f32_32x32x16_bf16 v[16:31], v[160:163], v[132:135], v[16:31]
	v_mfma_f32_32x32x16_bf16 v[0:15], v[160:163], v[136:139], v[0:15]
	v_mfma_f32_32x32x16_bf16 v[64:79], v[140:143], v[152:155], v[64:79]
	v_mfma_f32_32x32x16_bf16 v[112:127], v[140:143], v[156:159], v[112:127]
	s_nop 10
	v_cvt_pk_bf16_f32 v64, v64, v65
	v_cvt_pk_bf16_f32 v65, v66, v67
	v_cvt_pk_bf16_f32 v66, v68, v69
	v_cvt_pk_bf16_f32 v67, v70, v71
	ds_write2_b64 v168, v[64:65], v[66:67] offset1:2
	v_cvt_pk_bf16_f32 v64, v72, v73
	v_cvt_pk_bf16_f32 v65, v74, v75
	v_mfma_f32_32x32x16_bf16 v[96:111], v[144:147], v[152:155], v[96:111]
	v_cvt_pk_bf16_f32 v66, v76, v77
	v_cvt_pk_bf16_f32 v67, v78, v79
	ds_write2_b64 v168, v[64:65], v[66:67] offset0:4 offset1:6
	v_cvt_pk_bf16_f32 v64, v112, v113
	v_cvt_pk_bf16_f32 v65, v114, v115
	v_cvt_pk_bf16_f32 v66, v116, v117
	v_cvt_pk_bf16_f32 v67, v118, v119
	v_mfma_f32_32x32x16_bf16 v[32:47], v[128:131], v[156:159], v[32:47]
	v_add_u32_e32 v68, 0x2000, v168
	ds_write2_b64 v68, v[64:65], v[66:67] offset0:64 offset1:66
	v_cvt_pk_bf16_f32 v64, v120, v121
	v_cvt_pk_bf16_f32 v65, v122, v123
	v_cvt_pk_bf16_f32 v66, v124, v125
	v_cvt_pk_bf16_f32 v67, v126, v127
	ds_write2_b64 v68, v[64:65], v[66:67] offset0:68 offset1:70
	v_mfma_f32_32x32x16_bf16 v[80:95], v[144:147], v[156:159], v[80:95]
	v_cvt_pk_bf16_f32 v64, v96, v97
	v_cvt_pk_bf16_f32 v65, v98, v99
	v_cvt_pk_bf16_f32 v66, v100, v101
	v_cvt_pk_bf16_f32 v67, v102, v103
	ds_write2_b64 v168, v[64:65], v[66:67] offset0:8 offset1:10
	v_cvt_pk_bf16_f32 v64, v104, v105
	v_cvt_pk_bf16_f32 v65, v106, v107
	v_mfma_f32_32x32x16_bf16 v[48:63], v[128:131], v[152:155], v[48:63]
	v_cvt_pk_bf16_f32 v66, v108, v109
	v_cvt_pk_bf16_f32 v67, v110, v111
	v_cvt_pk_bf16_f32 v32, v32, v33
	v_cvt_pk_bf16_f32 v33, v34, v35
	v_cvt_pk_bf16_f32 v34, v36, v37
	v_cvt_pk_bf16_f32 v35, v38, v39
	ds_write2_b64 v168, v[64:65], v[66:67] offset0:12 offset1:14
	v_mfma_f32_32x32x16_bf16 v[16:31], v[148:151], v[152:155], v[16:31]
	v_cvt_pk_bf16_f32 v64, v80, v81
	v_cvt_pk_bf16_f32 v65, v82, v83
	v_cvt_pk_bf16_f32 v66, v84, v85
	v_cvt_pk_bf16_f32 v67, v86, v87
	v_cvt_pk_bf16_f32 v48, v48, v49
	v_cvt_pk_bf16_f32 v49, v50, v51
	v_cvt_pk_bf16_f32 v50, v52, v53
	v_mfma_f32_32x32x16_bf16 v[0:15], v[148:151], v[156:159], v[0:15]
	v_cvt_pk_bf16_f32 v51, v54, v55
	ds_write2_b64 v68, v[32:33], v[34:35] offset0:80 offset1:82
	v_cvt_pk_bf16_f32 v32, v40, v41
	v_cvt_pk_bf16_f32 v33, v42, v43
	v_cvt_pk_bf16_f32 v34, v44, v45
	v_cvt_pk_bf16_f32 v35, v46, v47
	v_cvt_pk_bf16_f32 v16, v16, v17
	v_cvt_pk_bf16_f32 v17, v18, v19
	v_cvt_pk_bf16_f32 v18, v20, v21
	v_cvt_pk_bf16_f32 v19, v22, v23
	s_nop 1
	v_cvt_pk_bf16_f32 v0, v0, v1
	v_cvt_pk_bf16_f32 v1, v2, v3
	v_cvt_pk_bf16_f32 v2, v4, v5
	v_cvt_pk_bf16_f32 v3, v6, v7
	v_ashrrev_i32_e32 v6, 4, v176
	ds_write2_b64 v68, v[64:65], v[66:67] offset0:72 offset1:74
	v_cvt_pk_bf16_f32 v64, v88, v89
	v_cvt_pk_bf16_f32 v65, v90, v91
	v_cvt_pk_bf16_f32 v66, v92, v93
	v_cvt_pk_bf16_f32 v67, v94, v95
	ds_write2_b64 v168, v[48:49], v[50:51] offset0:16 offset1:18
	v_cvt_pk_bf16_f32 v48, v56, v57
	v_cvt_pk_bf16_f32 v49, v58, v59
	v_cvt_pk_bf16_f32 v50, v60, v61
	v_cvt_pk_bf16_f32 v51, v62, v63
	ds_write2_b64 v68, v[32:33], v[34:35] offset0:84 offset1:86
	ds_write2_b64 v168, v[16:17], v[18:19] offset0:24 offset1:26
	v_cvt_pk_bf16_f32 v16, v24, v25
	v_cvt_pk_bf16_f32 v17, v26, v27
	v_cvt_pk_bf16_f32 v18, v28, v29
	v_cvt_pk_bf16_f32 v19, v30, v31
	ds_write2_b64 v68, v[0:1], v[2:3] offset0:88 offset1:90
	v_cvt_pk_bf16_f32 v0, v8, v9
	v_cvt_pk_bf16_f32 v1, v10, v11
	v_cvt_pk_bf16_f32 v2, v12, v13
	v_cvt_pk_bf16_f32 v3, v14, v15
	v_lshl_add_u64 v[32:33], s[4:5], 0, v[172:173]
	v_mad_u64_u32 v[4:5], s[4:5], v6, s36, v[172:173]
	ds_write2_b64 v68, v[64:65], v[66:67] offset0:76 offset1:78
	ds_write2_b64 v168, v[48:49], v[50:51] offset0:20 offset1:22
	ds_write2_b64 v168, v[16:17], v[18:19] offset0:28 offset1:30
	ds_write2_b64 v68, v[0:1], v[2:3] offset0:92 offset1:94
	s_waitcnt lgkmcnt(0)
	s_barrier
; template <bool IN_PROJ>
; DI void gemm_tile(const Params& p, int layer, int nt, int tt, char* smem) {
;     ...
; #pragma unroll
;     for (int hf = 0; hf < 2; ++hf) {
;       const u16* sH = (const u16*)(smem + hf * 34816);
; #pragma unroll
;       for (int i = 0; i < 8; ++i) {
;         int c = tid + 256 * i; int row = c >> 4, cc = c & 15;
;         u32x4 v = *(const u32x4*)(sH + row * CS + cc * 8);
;         *(u32x4*)(yb + (size_t)(t0 + row) * DM + n0 + hf * 128 + cc * 8) = v;
;       }
;     }
	ds_read_b128 v[0:3], v4
	v_add_u32_e32 v6, s2, v6
	v_ashrrev_i32_e32 v7, 31, v6
	v_lshlrev_b64 v[6:7], 11, v[6:7]
	v_ashrrev_i32_e32 v10, 4, v177
	v_lshl_add_u64 v[36:37], v[32:33], 0, v[6:7]
	v_mad_u64_u32 v[8:9], s[4:5], v10, s36, v[172:173]
	s_waitcnt lgkmcnt(0)
	global_store_dwordx4 v[36:37], v[0:3], off
	ds_read_b128 v[0:3], v8
	v_add_u32_e32 v10, s2, v10
	v_ashrrev_i32_e32 v11, 31, v10
	v_lshlrev_b64 v[10:11], 11, v[10:11]
	v_lshl_add_u64 v[38:39], v[32:33], 0, v[10:11]
	s_waitcnt lgkmcnt(0)
	global_store_dwordx4 v[38:39], v[0:3], off
	ds_read_b128 v[4:7], v4 offset:34816
	ds_read_b128 v[8:11], v8 offset:34816
	v_add_u32_e32 v0, 0x200, v176
	v_ashrrev_i32_e32 v14, 4, v0
	v_mad_u64_u32 v[12:13], s[4:5], v14, s36, v[172:173]
	ds_read_b128 v[0:3], v12
	v_add_u32_e32 v14, s2, v14
	v_ashrrev_i32_e32 v15, 31, v14
	v_lshlrev_b64 v[14:15], 11, v[14:15]
	v_lshl_add_u64 v[40:41], v[32:33], 0, v[14:15]
	s_waitcnt lgkmcnt(0)
	global_store_dwordx4 v[40:41], v[0:3], off
	ds_read_b128 v[12:15], v12 offset:34816
	s_nop 0
	v_add_u32_e32 v0, 0x300, v176
	v_ashrrev_i32_e32 v18, 4, v0
	v_mad_u64_u32 v[16:17], s[4:5], v18, s36, v[172:173]
	ds_read_b128 v[0:3], v16
	v_add_u32_e32 v18, s2, v18
	v_ashrrev_i32_e32 v19, 31, v18
	v_lshlrev_b64 v[18:19], 11, v[18:19]
	v_lshl_add_u64 v[42:43], v[32:33], 0, v[18:19]
	s_waitcnt lgkmcnt(0)
	global_store_dwordx4 v[42:43], v[0:3], off
	ds_read_b128 v[16:19], v16 offset:34816
	s_nop 0
	v_add_u32_e32 v0, 0x400, v176
	v_ashrrev_i32_e32 v22, 4, v0
	v_mad_u64_u32 v[20:21], s[4:5], v22, s36, v[172:173]
	ds_read_b128 v[0:3], v20
	v_add_u32_e32 v22, s2, v22
	v_ashrrev_i32_e32 v23, 31, v22
	v_lshlrev_b64 v[22:23], 11, v[22:23]
	v_lshl_add_u64 v[44:45], v[32:33], 0, v[22:23]
	s_waitcnt lgkmcnt(0)
	global_store_dwordx4 v[44:45], v[0:3], off
	ds_read_b128 v[20:23], v20 offset:34816
	s_nop 0
	v_add_u32_e32 v0, 0x500, v176
	v_ashrrev_i32_e32 v26, 4, v0
	v_mad_u64_u32 v[24:25], s[4:5], v26, s36, v[172:173]
	ds_read_b128 v[0:3], v24
	v_add_u32_e32 v26, s2, v26
	v_ashrrev_i32_e32 v27, 31, v26
	v_lshlrev_b64 v[26:27], 11, v[26:27]
	v_lshl_add_u64 v[46:47], v[32:33], 0, v[26:27]
	s_waitcnt lgkmcnt(0)
	global_store_dwordx4 v[46:47], v[0:3], off
	ds_read_b128 v[24:27], v24 offset:34816
	s_nop 0
	v_add_u32_e32 v0, 0x600, v176
	v_ashrrev_i32_e32 v30, 4, v0
	v_mad_u64_u32 v[28:29], s[4:5], v30, s36, v[172:173]
	ds_read_b128 v[0:3], v28
	v_add_u32_e32 v30, s2, v30
	v_ashrrev_i32_e32 v31, 31, v30
	v_lshlrev_b64 v[30:31], 11, v[30:31]
	v_lshl_add_u64 v[48:49], v[32:33], 0, v[30:31]
	s_waitcnt lgkmcnt(0)
	global_store_dwordx4 v[48:49], v[0:3], off
	ds_read_b128 v[28:31], v28 offset:34816
	s_nop 0
	v_add_u32_e32 v0, 0x700, v176
	v_ashrrev_i32_e32 v50, 4, v0
	v_mad_u64_u32 v[34:35], s[4:5], v50, s36, v[172:173]
	ds_read_b128 v[0:3], v34
	v_add_u32_e32 v50, s2, v50
	v_ashrrev_i32_e32 v51, 31, v50
	v_lshlrev_b64 v[50:51], 11, v[50:51]
	v_lshl_add_u64 v[50:51], v[32:33], 0, v[50:51]
	s_mov_b64 s[2:3], 0
	ds_read_b128 v[32:35], v34 offset:34816
	s_waitcnt lgkmcnt(1)
	global_store_dwordx4 v[50:51], v[0:3], off
	global_store_dwordx4 v[36:37], v[4:7], off offset:256
	global_store_dwordx4 v[38:39], v[8:11], off offset:256
	global_store_dwordx4 v[40:41], v[12:15], off offset:256
	global_store_dwordx4 v[42:43], v[16:19], off offset:256
	global_store_dwordx4 v[44:45], v[20:23], off offset:256
	global_store_dwordx4 v[46:47], v[24:27], off offset:256
	global_store_dwordx4 v[48:49], v[28:31], off offset:256
	s_waitcnt lgkmcnt(0)
	global_store_dwordx4 v[50:51], v[32:35], off offset:256

; template <bool IN_PROJ>
; DI void gemm_tile(const Params& p, int layer, int nt, int tt, char* smem) {
;     ...
;   auto stage = [&](int kt) {
;     const int k0 = kt * 32;
;     char* base = smem + (kt % 3) * G_STAGE + w * 1024;
; #pragma unroll
;     for (int i = 0; i < 4; ++i)
;       __builtin_amdgcn_raw_ptr_buffer_load_lds(rA, (lds_ptr_t)(base + i * 4096), 16, voA[i], k0 * 2, 0, 0);
; #pragma unroll
;     for (int i = 0; i < 2; ++i) {
;       lds_ptr_t dst = (lds_ptr_t)(base + 16384 + i * 4096);
;       if (IN_PROJ) __builtin_amdgcn_raw_ptr_buffer_load_lds(rB0, dst, 16, rowB[i] * (DM * 2) + lcB[i], k0 * 2, 0, 0);
;       else {
;         if (k0 < 512) __builtin_amdgcn_raw_ptr_buffer_load_lds(rB0, dst, 16, rowB[i] * 1024 + lcB[i], k0 * 2, 0, 0);
;         else if (k0 < 768) __builtin_amdgcn_raw_ptr_buffer_load_lds(rB1, dst, 16, rowB[i] * 512 + lcB[i], (k0 - 512) * 2, 0, 0);
;         else __builtin_amdgcn_raw_ptr_buffer_load_lds(rB2, dst, 16, rowB[i] * 512 + lcB[i], (k0 - 768) * 2, 0, 0);
;       }
;     }
;   };
;   asm volatile("s_waitcnt vmcnt(0)" ::: "memory");
;   __syncthreads();
;   stage(0); stage(1); stage(2);
;   auto load_frags = [&](int kt, int ks, bf16x8 (&fa)[4], bf16x8 (&fb)[2]) {
;     const u16* sA = (const u16*)(smem + (kt % 3) * G_STAGE);
;     const u16* sB = sA + 8192;
; #pragma unroll
;     for (int fi = 0; fi < 4; ++fi) fa[fi] = *(const bf16x8*)(sA + gswz(wf * 128 + fi * 32 + r, ks * 2 + h));
; #pragma unroll
;     for (int ti = 0; ti < 2; ++ti) fb[ti] = *(const bf16x8*)(sB + gswz(wt * 64 + ti * 32 + r, ks * 2 + h));
;   };
;   auto mma = [&](const bf16x8 (&fa)[4], const bf16x8 (&fb)[2]) {
; #pragma unroll
;     for (int fi = 0; fi < 4; ++fi)
; #pragma unroll
;       for (int ti = 0; ti < 2; ++ti) acc[fi][ti] = MFMA32(fa[fi], fb[ti], acc[fi][ti]);
;   };
;   bf16x8 fa0[4], fb0[2], fa1[4], fb1[2];
;   asm volatile("s_waitcnt vmcnt(12)" ::: "memory");
;   __syncthreads();
;   load_frags(0, 0, fa0, fb0);
;   for (int kt = 0; kt < 32; ++kt) {
;     load_frags(kt, 1, fa1, fb1);
;     mma(fa0, fb0);
;     if (kt + 1 < 32) {
;       if (kt + 2 < 32) asm volatile("s_waitcnt vmcnt(6) lgkmcnt(0)" ::: "memory");
;       else asm volatile("s_waitcnt vmcnt(0) lgkmcnt(0)" ::: "memory");
;       __syncthreads();
;       if (kt + 3 < 32) stage(kt + 3);
;       load_frags(kt + 1, 0, fa0, fb0);
;     }
;     mma(fa1, fb1);
;   }
.LBB0_791:
	s_mul_i32 s3, s0, 0xab
	s_add_i32 s10, s3, 0xfdff
	s_bfe_u32 s10, s10, 0x70009
	s_mul_i32 s10, s10, 3
	s_sub_i32 s10, s0, s10
	s_add_i32 s10, s10, 0xfffd
	s_and_b32 s10, s10, 0xff
	s_mulk_i32 s10, 0x6000
	v_lshl_add_u32 v136, v188, 1, s10
	ds_read_b128 v[172:175], v136
	v_lshl_add_u32 v136, v186, 1, s10
	v_lshl_or_b32 v140, v187, 1, s10
	ds_read_b128 v[168:171], v136 offset:2048
	ds_read_b128 v[164:167], v136 offset:4096
	ds_read_b128 v[136:139], v136 offset:6144
	ds_read_b128 v[160:163], v140 offset:16384
	v_lshl_or_b32 v140, v180, 1, s10
	s_bfe_u32 s10, s3, 0x70009
	s_mul_i32 s10, s10, 3
	s_sub_i32 s10, s0, s10
	s_and_b32 s10, s10, 0xff
	s_mulk_i32 s10, 0x6000
	s_add_i32 s13, s1, s10
	s_mov_b32 m0, s13
	ds_read_b128 v[140:143], v140 offset:18432
	s_waitcnt vmcnt(6) lgkmcnt(0)
	s_waitcnt lgkmcnt(0)
	s_barrier
	buffer_load_dwordx4 v181, s[4:7], s2 offen lds
	s_add_i32 m0, s13, 0x1000
	s_mov_b32 s10, s6
	buffer_load_dwordx4 v182, s[4:7], s2 offen lds
	s_add_i32 m0, s13, 0x2000
	s_mov_b32 s11, s7
	buffer_load_dwordx4 v183, s[4:7], s2 offen lds
	s_add_i32 m0, s13, 0x3000
	v_mfma_f32_32x32x16_bf16 v[64:79], v[132:135], v[128:131], v[64:79]
	buffer_load_dwordx4 v184, s[4:7], s2 offen lds
	s_add_i32 m0, s13, 0x4000
	s_add_i32 s3, s3, 0xfeaa
	buffer_load_dwordx4 v181, s[8:11], s2 offen lds
	s_add_i32 m0, s13, 0x5000
	s_bfe_u32 s3, s3, 0x70009
	buffer_load_dwordx4 v185, s[8:11], s2 offen lds
	v_mfma_f32_32x32x16_bf16 v[0:15], v[132:135], v[108:111], v[0:15]
	s_mul_i32 s3, s3, 3
	s_sub_i32 s3, s0, s3
	s_add_i32 s3, s3, 0xfffe
	s_and_b32 s3, s3, 0xff
	s_mulk_i32 s3, 0x6000
	s_add_i32 s2, s2, 64
	s_add_i32 s0, s0, 1
	v_mfma_f32_32x32x16_bf16 v[80:95], v[104:107], v[128:131], v[80:95]
	s_cmp_eq_u32 s0, 32
	v_mfma_f32_32x32x16_bf16 v[16:31], v[104:107], v[108:111], v[16:31]
	v_mfma_f32_32x32x16_bf16 v[112:127], v[100:103], v[128:131], v[112:127]
	v_mfma_f32_32x32x16_bf16 v[32:47], v[100:103], v[108:111], v[32:47]
	v_mfma_f32_32x32x16_bf16 v[144:159], v[96:99], v[128:131], v[144:159]
	v_mfma_f32_32x32x16_bf16 v[48:63], v[96:99], v[108:111], v[48:63]
	v_lshl_add_u32 v96, v189, 1, s3
	ds_read_b128 v[132:135], v96
	v_lshl_add_u32 v96, v190, 1, s3
	v_lshl_or_b32 v108, v191, 1, s3
	ds_read_b128 v[104:107], v96 offset:2048
	ds_read_b128 v[100:103], v96 offset:4096
	ds_read_b128 v[96:99], v96 offset:6144
	ds_read_b128 v[128:131], v108 offset:16384
	v_lshl_or_b32 v108, v192, 1, s3
	v_mfma_f32_32x32x16_bf16 v[64:79], v[172:175], v[160:163], v[64:79]
	ds_read_b128 v[108:111], v108 offset:18432
	v_mfma_f32_32x32x16_bf16 v[0:15], v[172:175], v[140:143], v[0:15]
	v_mfma_f32_32x32x16_bf16 v[80:95], v[168:171], v[160:163], v[80:95]
	v_mfma_f32_32x32x16_bf16 v[16:31], v[168:171], v[140:143], v[16:31]
	v_mfma_f32_32x32x16_bf16 v[112:127], v[164:167], v[160:163], v[112:127]
	v_mfma_f32_32x32x16_bf16 v[32:47], v[164:167], v[140:143], v[32:47]
	v_mfma_f32_32x32x16_bf16 v[144:159], v[136:139], v[160:163], v[144:159]
	v_mfma_f32_32x32x16_bf16 v[48:63], v[136:139], v[140:143], v[48:63]
	s_cbranch_scc0 .LBB0_791
	s_waitcnt lgkmcnt(1)
	v_mfma_f32_32x32x16_bf16 v[64:79], v[132:135], v[128:131], v[64:79]
	s_lshl_b32 s15, s14, 1
	s_add_i32 s1, s72, s15
	s_mov_b64 s[8:9], -1
	s_cmp_gt_i32 s1, 3
	v_mfma_f32_32x32x16_bf16 v[80:95], v[104:107], v[128:131], v[80:95]
	v_mfma_f32_32x32x16_bf16 v[112:127], v[100:103], v[128:131], v[112:127]
	v_mfma_f32_32x32x16_bf16 v[144:159], v[96:99], v[128:131], v[144:159]
	v_lshlrev_b32_e32 v128, 1, v188
	v_lshlrev_b32_e32 v130, 1, v186
	v_lshlrev_b32_e32 v129, 1, v187
	s_waitcnt lgkmcnt(0)
	v_mfma_f32_32x32x16_bf16 v[16:31], v[104:107], v[108:111], v[16:31]
	ds_read_b128 v[104:107], v130 offset:51200
	v_mfma_f32_32x32x16_bf16 v[32:47], v[100:103], v[108:111], v[32:47]
	ds_read_b128 v[100:103], v128 offset:49152
	v_mfma_f32_32x32x16_bf16 v[0:15], v[132:135], v[108:111], v[0:15]
	v_mfma_f32_32x32x16_bf16 v[48:63], v[96:99], v[108:111], v[48:63]
	v_or_b32_e32 v96, 0x10000, v129
	v_lshl_or_b32 v108, v180, 1, v244
	ds_read_b128 v[96:99], v96
	ds_read_b128 v[108:111], v108
	s_waitcnt lgkmcnt(1)
	v_mfma_f32_32x32x16_bf16 v[64:79], v[100:103], v[96:99], v[64:79]
	s_waitcnt lgkmcnt(0)
	v_mfma_f32_32x32x16_bf16 v[0:15], v[100:103], v[108:111], v[0:15]
	v_mfma_f32_32x32x16_bf16 v[80:95], v[104:107], v[96:99], v[80:95]
	v_mfma_f32_32x32x16_bf16 v[16:31], v[104:107], v[108:111], v[16:31]
	ds_read_b128 v[100:103], v130 offset:53248
	ds_read_b128 v[104:107], v130 offset:55296
	s_waitcnt vmcnt(6) lgkmcnt(0)
	s_waitcnt lgkmcnt(0)
	s_barrier
; DI TileDesc tile_desc(const Params& p, int nt) {
;   TileDesc d; d.aux = 0;
;   char* ws = p.ws; char* o = p.out;
;   if (nt < 4)       { d.kind = K_SILU; d.dst = (u16*)(ws + WS_HQ); d.stride = 512; d.col = nt * 128; }
;   else if (nt < 8)  { d.kind = K_G;    d.dst = (u16*)(ws + WS_GF); d.stride = 512; d.col = (nt - 4) * 128; d.aux = 0; }
;   else if (nt < 12) { d.kind = K_G;    d.dst = (u16*)(ws + WS_GB); d.stride = 512; d.col = (nt - 8) * 128; d.aux = 1; }
;   else if (nt < 16) { d.kind = K_COPY; d.dst = (u16*)(ws + WS_HV); d.stride = 512; d.col = (nt - 12) * 128; }
;   else if (nt < 20) { d.kind = K_SILU; d.dst = (u16*)(o + DO_GA);  d.stride = 512; d.col = (nt - 16) * 128; }
;   else if (nt < 22) { d.kind = K_QN;   d.dst = (u16*)(o + DO_BQ);  d.stride = 256; d.col = (nt - 20) * 128; }
;   else if (nt < 23) { d.kind = K_KN;   d.dst = (u16*)(o + DO_BK);  d.stride = 128; d.col = 0; }
;   else if (nt < 24) { d.kind = K_VT;   d.dst = (u16*)(o + DO_BVT); d.stride = T_TOK; d.col = 0; }
;   else if (nt < 26) { d.kind = K_SILU; d.dst = (u16*)(o + DO_GB);  d.stride = 256; d.col = (nt - 24) * 128; }
;   else if (nt < 28) { d.kind = K_CQ;   d.dst = (u16*)(o + DO_CQ);  d.stride = 256; d.col = (nt - 26) * 128; }
;   else if (nt < 30) { d.kind = K_CK;   d.dst = (u16*)(o + DO_CK);  d.stride = 256; d.col = (nt - 28) * 128; d.aux = (nt - 28); }
;   else if (nt < 32) { d.kind = K_VT;   d.dst = (u16*)(ws + WS_CVT); d.stride = T_TOK; d.col = (nt - 30) * 128; }
;   else              { d.kind = K_SILU; d.dst = (u16*)(o + DO_GC);  d.stride = 256; d.col = (nt - 32) * 128; }
;   return d;
; template <bool IN_PROJ>
; DI void gemm_tile(const Params& p, int layer, int nt, int tt, char* smem) {
;     ...
;   for (int kt = 0; kt < 32; ++kt) {
;     load_frags(kt, 1, fa1, fb1);
;     mma(fa0, fb0);
;     if (kt + 1 < 32) {
;       if (kt + 2 < 32) asm volatile("s_waitcnt vmcnt(6) lgkmcnt(0)" ::: "memory");
;       else asm volatile("s_waitcnt vmcnt(0) lgkmcnt(0)" ::: "memory");
;       __syncthreads();
;       if (kt + 3 < 32) stage(kt + 3);
;       load_frags(kt + 1, 0, fa0, fb0);
;     }
;     mma(fa1, fb1);
;   }
;   __syncthreads();
	v_mfma_f32_32x32x16_bf16 v[112:127], v[100:103], v[96:99], v[112:127]
	v_mfma_f32_32x32x16_bf16 v[32:47], v[100:103], v[108:111], v[32:47]
	v_mfma_f32_32x32x16_bf16 v[144:159], v[104:107], v[96:99], v[144:159]
	ds_read_b128 v[96:99], v177
	ds_read_b128 v[100:103], v178 offset:16384
	v_mfma_f32_32x32x16_bf16 v[48:63], v[104:107], v[108:111], v[48:63]
	ds_read_b128 v[104:107], v179 offset:18432
	v_lshlrev_b32_e32 v108, 1, v180
	s_waitcnt lgkmcnt(1)
	v_mfma_f32_32x32x16_bf16 v[64:79], v[96:99], v[100:103], v[64:79]
	s_waitcnt lgkmcnt(0)
	v_mfma_f32_32x32x16_bf16 v[0:15], v[96:99], v[104:107], v[0:15]
	ds_read_b128 v[96:99], v176 offset:2048
	s_waitcnt lgkmcnt(0)
	v_mfma_f32_32x32x16_bf16 v[80:95], v[96:99], v[100:103], v[80:95]
	v_mfma_f32_32x32x16_bf16 v[16:31], v[96:99], v[104:107], v[16:31]
	ds_read_b128 v[96:99], v176 offset:4096
	s_waitcnt lgkmcnt(0)
	v_mfma_f32_32x32x16_bf16 v[112:127], v[96:99], v[100:103], v[112:127]
	v_mfma_f32_32x32x16_bf16 v[32:47], v[96:99], v[104:107], v[32:47]
	ds_read_b128 v[96:99], v176 offset:6144
	s_waitcnt lgkmcnt(0)
	v_mfma_f32_32x32x16_bf16 v[144:159], v[96:99], v[100:103], v[144:159]
	v_mfma_f32_32x32x16_bf16 v[48:63], v[96:99], v[104:107], v[48:63]
	ds_read_b128 v[96:99], v128
	ds_read_b128 v[100:103], v129 offset:16384
	ds_read_b128 v[104:107], v108 offset:18432
	s_waitcnt lgkmcnt(1)
	v_mfma_f32_32x32x16_bf16 v[64:79], v[96:99], v[100:103], v[64:79]
	s_waitcnt lgkmcnt(0)
	v_mfma_f32_32x32x16_bf16 v[0:15], v[96:99], v[104:107], v[0:15]
	ds_read_b128 v[96:99], v130 offset:2048
	s_waitcnt lgkmcnt(0)
	v_mfma_f32_32x32x16_bf16 v[80:95], v[96:99], v[100:103], v[80:95]
	v_mfma_f32_32x32x16_bf16 v[16:31], v[96:99], v[104:107], v[16:31]
	ds_read_b128 v[96:99], v130 offset:4096
	s_waitcnt lgkmcnt(0)
	v_mfma_f32_32x32x16_bf16 v[112:127], v[96:99], v[100:103], v[112:127]
	v_mfma_f32_32x32x16_bf16 v[32:47], v[96:99], v[104:107], v[32:47]
	ds_read_b128 v[96:99], v130 offset:6144
	s_waitcnt vmcnt(0) lgkmcnt(0)
	s_waitcnt lgkmcnt(0)
	s_barrier
	v_mfma_f32_32x32x16_bf16 v[144:159], v[96:99], v[100:103], v[144:159]
	v_mfma_f32_32x32x16_bf16 v[48:63], v[96:99], v[104:107], v[48:63]
	ds_read_b128 v[96:99], v177 offset:24576
	ds_read_b128 v[100:103], v178 offset:40960
	ds_read_b128 v[104:107], v179 offset:43008
	s_waitcnt lgkmcnt(1)
	v_mfma_f32_32x32x16_bf16 v[64:79], v[96:99], v[100:103], v[64:79]
	s_waitcnt lgkmcnt(0)
	v_mfma_f32_32x32x16_bf16 v[0:15], v[96:99], v[104:107], v[0:15]
	ds_read_b128 v[96:99], v176 offset:26624
	s_waitcnt lgkmcnt(0)
	v_mfma_f32_32x32x16_bf16 v[80:95], v[96:99], v[100:103], v[80:95]
	v_mfma_f32_32x32x16_bf16 v[16:31], v[96:99], v[104:107], v[16:31]
	ds_read_b128 v[96:99], v176 offset:28672
	s_waitcnt lgkmcnt(0)
	v_mfma_f32_32x32x16_bf16 v[112:127], v[96:99], v[100:103], v[112:127]
	v_mfma_f32_32x32x16_bf16 v[32:47], v[96:99], v[104:107], v[32:47]
	ds_read_b128 v[96:99], v176 offset:30720
	s_waitcnt lgkmcnt(0)
	v_mfma_f32_32x32x16_bf16 v[144:159], v[96:99], v[100:103], v[144:159]
	v_mfma_f32_32x32x16_bf16 v[48:63], v[96:99], v[104:107], v[48:63]
	ds_read_b128 v[96:99], v128 offset:24576
	ds_read_b128 v[100:103], v129 offset:40960
	ds_read_b128 v[104:107], v130 offset:26624
	ds_read_b128 v[108:111], v108 offset:43008
	s_waitcnt lgkmcnt(2)
	v_mfma_f32_32x32x16_bf16 v[64:79], v[96:99], v[100:103], v[64:79]
	s_waitcnt lgkmcnt(0)
	v_mfma_f32_32x32x16_bf16 v[0:15], v[96:99], v[108:111], v[0:15]
	v_mfma_f32_32x32x16_bf16 v[80:95], v[104:107], v[100:103], v[80:95]
	v_mfma_f32_32x32x16_bf16 v[16:31], v[104:107], v[108:111], v[16:31]
	ds_read_b128 v[96:99], v130 offset:28672
	ds_read_b128 v[104:107], v130 offset:30720
	s_waitcnt lgkmcnt(0)
	s_barrier
	v_mfma_f32_32x32x16_bf16 v[112:127], v[96:99], v[100:103], v[112:127]
	v_mfma_f32_32x32x16_bf16 v[32:47], v[96:99], v[108:111], v[32:47]
	v_mfma_f32_32x32x16_bf16 v[144:159], v[104:107], v[100:103], v[144:159]
	v_mfma_f32_32x32x16_bf16 v[48:63], v[104:107], v[108:111], v[48:63]
	s_cbranch_scc0 .LBB0_832
	s_cmp_gt_u32 s1, 7
	s_cbranch_scc0 .LBB0_829
	s_cmp_gt_u32 s1, 11
	s_mov_b64 s[4:5], -1
	s_cbranch_scc0 .LBB0_827
	s_cmp_gt_u32 s1, 15
	s_cbranch_scc0 .LBB0_824
	s_cmp_gt_u32 s1, 19
	s_cbranch_scc0 .LBB0_821
	s_cmp_gt_u32 s1, 21
	s_cbranch_scc0 .LBB0_818
	s_cmp_eq_u32 s1, 22
	s_mov_b64 s[4:5], 0
	s_cbranch_scc1 .LBB0_814
	s_cmp_lt_u32 s1, 24
	s_cbranch_scc1 .LBB0_815
	s_cmp_gt_u32 s1, 25
	s_cbranch_scc0 .LBB0_812
	s_cmp_gt_u32 s1, 27
	s_cbranch_scc0 .LBB0_809
	s_cmp_gt_u32 s1, 29
	s_mov_b64 s[10:11], -1
	s_cbranch_scc0 .LBB0_807
	s_lshl_b32 s8, s1, 7
	s_cmp_gt_u32 s1, 31
	s_mov_b64 s[2:3], -1
	s_cbranch_scc0 .LBB0_805
	s_add_i32 s0, s8, 0xfffff000
	s_mov_b64 s[2:3], 0
